# v012 + nt on phase-5 final out stores (write-once)
# speedup vs baseline: 1.0147x; 1.0035x over previous
; __device__ __forceinline__ void phase5(const Args& a, int bid, int G) {
;     ...
;     for (int m = gw; m < T; m += NGW) {
;         const float tot = wave_sum(rsq[(size_t)m * 64 + lane]);
;         const float rstd = __builtin_amdgcn_rsqf(tot * (1.0f / DM) + EPS);
;         const u32x4* yr = (const u32x4*)(Y + (size_t)m * LDP) + lane;
;         f32x4* orow = (f32x4*)(a.out + (size_t)m * DM) + 2 * lane;
;         u32x4 v[8];
; #pragma unroll
;         for (int j = 0; j < 8; ++j) v[j] = yr[64 * j];
; #pragma unroll
;         for (int j = 0; j < 8; ++j) { const f32x4 w0 = *((const f32x4*)a.fin_w + 2 * lane + 128 * j), w1 = *((const f32x4*)a.fin_w + 2 * lane + 128 * j + 1);
;             orow[128 * j] = (f32x4){bflo(v[j].x) * rstd * w0[0], bfhi(v[j].x) * rstd * w0[1], bflo(v[j].y) * rstd * w0[2], bfhi(v[j].y) * rstd * w0[3]};
;             orow[128 * j + 1] = (f32x4){bflo(v[j].z) * rstd * w1[0], bfhi(v[j].z) * rstd * w1[1], bflo(v[j].w) * rstd * w1[2], bfhi(v[j].w) * rstd * w1[3]}; }
;     }
.LBB0_617:
	v_lshl_add_u64 v[0:1], s[30:31], 0, v[28:29]
	global_load_dwordx4 v[40:43], v[12:13], off offset:16
	global_load_dwordx4 v[44:47], v[12:13], off
	global_load_dword v32, v[0:1], off
	v_lshl_add_u64 v[2:3], s[30:31], 0, v[30:31]
	v_add_co_u32_e32 v68, vcc, s1, v2
	s_add_i32 s8, s8, s0
	s_nop 0
	v_addc_co_u32_e32 v69, vcc, 0, v3, vcc
	v_add_co_u32_e32 v70, vcc, s9, v2
	v_lshl_add_u64 v[28:29], v[28:29], 0, s[4:5]
	s_nop 0
	v_addc_co_u32_e32 v71, vcc, 0, v3, vcc
	global_load_dwordx4 v[48:51], v[70:71], off offset:-4096
	global_load_dwordx4 v[52:55], v[68:69], off offset:1024
	global_load_dwordx4 v[56:59], v[68:69], off offset:2048
	global_load_dwordx4 v[60:63], v[68:69], off offset:3072
	global_load_dwordx4 v[64:67], v[70:71], off
	global_load_dwordx4 v[8:11], v[70:71], off offset:1024
	global_load_dwordx4 v[4:7], v[70:71], off offset:2048
	global_load_dwordx4 v[0:3], v[70:71], off offset:3072
	v_lshl_add_u64 v[30:31], v[30:31], 0, s[6:7]
	s_cmpk_lt_i32 s8, 0x4000
	s_waitcnt vmcnt(0)
	ds_bpermute_b32 v72, v33, v32
	v_lshlrev_b32_e32 v68, 16, v48
	s_waitcnt lgkmcnt(0)
	v_add_f32_e32 v32, v32, v72
	ds_bpermute_b32 v72, v34, v32
	v_and_b32_e32 v69, 0xffff0000, v48
	v_lshlrev_b32_e32 v48, 16, v49
	v_and_b32_e32 v49, 0xffff0000, v49
	v_lshlrev_b32_e32 v70, 16, v50
	s_waitcnt lgkmcnt(0)
	v_add_f32_e32 v32, v32, v72
	ds_bpermute_b32 v72, v35, v32
	v_and_b32_e32 v71, 0xffff0000, v50
	v_lshlrev_b32_e32 v50, 16, v51
	v_and_b32_e32 v51, 0xffff0000, v51
	s_waitcnt lgkmcnt(0)
	v_add_f32_e32 v32, v32, v72
	ds_bpermute_b32 v72, v36, v32
	s_waitcnt lgkmcnt(0)
	v_add_f32_e32 v32, v32, v72
	ds_bpermute_b32 v72, v37, v32
	s_waitcnt lgkmcnt(0)
	v_add_f32_e32 v32, v32, v72
	ds_bpermute_b32 v72, v38, v32
	s_waitcnt lgkmcnt(0)
	v_add_f32_e32 v32, v32, v72
	v_fmamk_f32 v32, v32, 0x39800000, v39
	v_rsq_f32_e32 v32, v32
	s_nop 0
	v_pk_mul_f32 v[68:69], v[32:33], v[68:69] op_sel_hi:[0,1]
	v_pk_mul_f32 v[48:49], v[32:33], v[48:49] op_sel_hi:[0,1]
	v_pk_mul_f32 v[70:71], v[32:33], v[70:71] op_sel_hi:[0,1]
	v_pk_mul_f32 v[50:51], v[32:33], v[50:51] op_sel_hi:[0,1]
	v_pk_mul_f32 v[44:45], v[68:69], v[44:45]
	v_pk_mul_f32 v[46:47], v[48:49], v[46:47]
	v_pk_mul_f32 v[40:41], v[70:71], v[40:41]
	v_pk_mul_f32 v[42:43], v[50:51], v[42:43]
	global_store_dwordx4 v[26:27], v[44:47], off nt
	global_store_dwordx4 v[26:27], v[40:43], off offset:16 nt
	global_load_dwordx4 v[40:43], v[12:13], off offset:2048
	s_nop 0
	global_load_dwordx4 v[44:47], v[12:13], off offset:2064
	v_lshlrev_b32_e32 v48, 16, v52
	v_and_b32_e32 v49, 0xffff0000, v52
	v_lshlrev_b32_e32 v50, 16, v53
	v_and_b32_e32 v51, 0xffff0000, v53
	v_lshlrev_b32_e32 v52, 16, v54
	v_and_b32_e32 v53, 0xffff0000, v54
	v_lshlrev_b32_e32 v54, 16, v55
	v_and_b32_e32 v55, 0xffff0000, v55
	v_pk_mul_f32 v[48:49], v[32:33], v[48:49] op_sel_hi:[0,1]
	v_pk_mul_f32 v[50:51], v[32:33], v[50:51] op_sel_hi:[0,1]
	v_pk_mul_f32 v[52:53], v[32:33], v[52:53] op_sel_hi:[0,1]
	v_pk_mul_f32 v[54:55], v[32:33], v[54:55] op_sel_hi:[0,1]
	s_waitcnt vmcnt(1)
	v_pk_mul_f32 v[40:41], v[48:49], v[40:41]
	v_pk_mul_f32 v[42:43], v[50:51], v[42:43]
	s_waitcnt vmcnt(0)
	v_pk_mul_f32 v[44:45], v[52:53], v[44:45]
	v_pk_mul_f32 v[46:47], v[54:55], v[46:47]
	global_store_dwordx4 v[26:27], v[40:43], off offset:2048 nt
	global_store_dwordx4 v[26:27], v[44:47], off offset:2064 nt
	global_load_dwordx4 v[40:43], v[14:15], off
	s_nop 0
	global_load_dwordx4 v[44:47], v[14:15], off offset:16
	v_add_co_u32_e32 v48, vcc, s10, v26
	v_lshlrev_b32_e32 v52, 16, v56
	s_nop 0
	v_addc_co_u32_e32 v49, vcc, 0, v27, vcc
	v_and_b32_e32 v53, 0xffff0000, v56
	v_lshlrev_b32_e32 v54, 16, v57
	v_and_b32_e32 v55, 0xffff0000, v57
	v_add_co_u32_e32 v50, vcc, s11, v26
	v_lshlrev_b32_e32 v56, 16, v58
	v_and_b32_e32 v57, 0xffff0000, v58
	v_lshlrev_b32_e32 v58, 16, v59
	v_and_b32_e32 v59, 0xffff0000, v59
	v_pk_mul_f32 v[52:53], v[32:33], v[52:53] op_sel_hi:[0,1]
	v_pk_mul_f32 v[54:55], v[32:33], v[54:55] op_sel_hi:[0,1]
	v_addc_co_u32_e32 v51, vcc, 0, v27, vcc
	v_pk_mul_f32 v[56:57], v[32:33], v[56:57] op_sel_hi:[0,1]
	v_pk_mul_f32 v[58:59], v[32:33], v[58:59] op_sel_hi:[0,1]
	s_waitcnt vmcnt(1)
	v_pk_mul_f32 v[40:41], v[52:53], v[40:41]
	v_pk_mul_f32 v[42:43], v[54:55], v[42:43]
	s_waitcnt vmcnt(0)
; __device__ __forceinline__ void phase5(const Args& a, int bid, int G) {
;     ...
;         for (int j = 0; j < 8; ++j) { const f32x4 w0 = *((const f32x4*)a.fin_w + 2 * lane + 128 * j), w1 = *((const f32x4*)a.fin_w + 2 * lane + 128 * j + 1);
;             orow[128 * j] = (f32x4){bflo(v[j].x) * rstd * w0[0], bfhi(v[j].x) * rstd * w0[1], bflo(v[j].y) * rstd * w0[2], bfhi(v[j].y) * rstd * w0[3]};
;             orow[128 * j + 1] = (f32x4){bflo(v[j].z) * rstd * w1[0], bfhi(v[j].z) * rstd * w1[1], bflo(v[j].w) * rstd * w1[2], bfhi(v[j].w) * rstd * w1[3]}; }
	v_pk_mul_f32 v[44:45], v[56:57], v[44:45]
	v_pk_mul_f32 v[46:47], v[58:59], v[46:47]
	global_store_dwordx4 v[50:51], v[40:43], off offset:-4096 nt
	global_store_dwordx4 v[48:49], v[44:47], off offset:16 nt
	global_load_dwordx4 v[40:43], v[16:17], off
	s_nop 0
	global_load_dwordx4 v[44:47], v[16:17], off offset:16
	v_lshlrev_b32_e32 v52, 16, v60
	v_and_b32_e32 v53, 0xffff0000, v60
	v_lshlrev_b32_e32 v54, 16, v61
	v_and_b32_e32 v55, 0xffff0000, v61
	v_lshlrev_b32_e32 v56, 16, v62
	v_and_b32_e32 v57, 0xffff0000, v62
	v_lshlrev_b32_e32 v58, 16, v63
	v_and_b32_e32 v59, 0xffff0000, v63
	v_pk_mul_f32 v[52:53], v[32:33], v[52:53] op_sel_hi:[0,1]
	v_pk_mul_f32 v[54:55], v[32:33], v[54:55] op_sel_hi:[0,1]
	v_pk_mul_f32 v[56:57], v[32:33], v[56:57] op_sel_hi:[0,1]
	v_pk_mul_f32 v[58:59], v[32:33], v[58:59] op_sel_hi:[0,1]
	s_waitcnt vmcnt(1)
	v_pk_mul_f32 v[40:41], v[52:53], v[40:41]
	v_pk_mul_f32 v[42:43], v[54:55], v[42:43]
	s_waitcnt vmcnt(0)
	v_pk_mul_f32 v[44:45], v[56:57], v[44:45]
	v_pk_mul_f32 v[46:47], v[58:59], v[46:47]
	global_store_dwordx4 v[48:49], v[40:43], off offset:2048 nt
	global_store_dwordx4 v[48:49], v[44:47], off offset:2064 nt
	global_load_dwordx4 v[40:43], v[18:19], off
	s_nop 0
	global_load_dwordx4 v[44:47], v[18:19], off offset:16
	v_lshlrev_b32_e32 v48, 16, v64
	v_and_b32_e32 v49, 0xffff0000, v64
	v_lshlrev_b32_e32 v52, 16, v65
	v_and_b32_e32 v53, 0xffff0000, v65
	v_lshlrev_b32_e32 v54, 16, v66
	v_and_b32_e32 v55, 0xffff0000, v66
	v_lshlrev_b32_e32 v56, 16, v67
	v_and_b32_e32 v57, 0xffff0000, v67
	v_pk_mul_f32 v[48:49], v[32:33], v[48:49] op_sel_hi:[0,1]
	v_pk_mul_f32 v[52:53], v[32:33], v[52:53] op_sel_hi:[0,1]
	v_pk_mul_f32 v[54:55], v[32:33], v[54:55] op_sel_hi:[0,1]
	v_pk_mul_f32 v[56:57], v[32:33], v[56:57] op_sel_hi:[0,1]
	s_waitcnt vmcnt(1)
	v_pk_mul_f32 v[40:41], v[48:49], v[40:41]
	v_pk_mul_f32 v[42:43], v[52:53], v[42:43]
	s_waitcnt vmcnt(0)
	v_pk_mul_f32 v[44:45], v[54:55], v[44:45]
	v_pk_mul_f32 v[46:47], v[56:57], v[46:47]
	global_store_dwordx4 v[50:51], v[40:43], off nt
	global_store_dwordx4 v[50:51], v[44:47], off offset:16 nt
	global_load_dwordx4 v[40:43], v[20:21], off
	s_nop 0
	global_load_dwordx4 v[44:47], v[20:21], off offset:16
	v_lshlrev_b32_e32 v48, 16, v8
	v_and_b32_e32 v49, 0xffff0000, v8
	v_lshlrev_b32_e32 v8, 16, v9
	v_and_b32_e32 v9, 0xffff0000, v9
	v_lshlrev_b32_e32 v52, 16, v10
	v_and_b32_e32 v53, 0xffff0000, v10
	v_lshlrev_b32_e32 v10, 16, v11
	v_and_b32_e32 v11, 0xffff0000, v11
	v_pk_mul_f32 v[48:49], v[32:33], v[48:49] op_sel_hi:[0,1]
	v_pk_mul_f32 v[54:55], v[32:33], v[8:9] op_sel_hi:[0,1]
	v_pk_mul_f32 v[52:53], v[32:33], v[52:53] op_sel_hi:[0,1]
	v_pk_mul_f32 v[56:57], v[32:33], v[10:11] op_sel_hi:[0,1]
	s_waitcnt vmcnt(1)
	v_pk_mul_f32 v[8:9], v[48:49], v[40:41]
	v_pk_mul_f32 v[10:11], v[54:55], v[42:43]
	s_waitcnt vmcnt(0)
	v_pk_mul_f32 v[40:41], v[52:53], v[44:45]
	v_pk_mul_f32 v[42:43], v[56:57], v[46:47]
	global_store_dwordx4 v[50:51], v[8:11], off offset:2048 nt
	global_store_dwordx4 v[50:51], v[40:43], off offset:2064 nt
	global_load_dwordx4 v[8:11], v[22:23], off
	s_nop 0
	global_load_dwordx4 v[40:43], v[22:23], off offset:16
	v_lshlrev_b32_e32 v46, 16, v4
	v_and_b32_e32 v47, 0xffff0000, v4
	v_lshlrev_b32_e32 v4, 16, v5
	v_and_b32_e32 v5, 0xffff0000, v5
	v_add_co_u32_e32 v44, vcc, s12, v26
	v_lshlrev_b32_e32 v48, 16, v6
	v_and_b32_e32 v49, 0xffff0000, v6
	v_lshlrev_b32_e32 v6, 16, v7
	v_and_b32_e32 v7, 0xffff0000, v7
	v_pk_mul_f32 v[46:47], v[32:33], v[46:47] op_sel_hi:[0,1]
	v_pk_mul_f32 v[50:51], v[32:33], v[4:5] op_sel_hi:[0,1]
	v_addc_co_u32_e32 v45, vcc, 0, v27, vcc
	v_pk_mul_f32 v[48:49], v[32:33], v[48:49] op_sel_hi:[0,1]
	v_pk_mul_f32 v[52:53], v[32:33], v[6:7] op_sel_hi:[0,1]
	v_lshl_add_u64 v[26:27], v[26:27], 0, s[2:3]
	s_waitcnt vmcnt(1)
	v_pk_mul_f32 v[4:5], v[46:47], v[8:9]
	v_pk_mul_f32 v[6:7], v[50:51], v[10:11]
	s_waitcnt vmcnt(0)
	v_pk_mul_f32 v[8:9], v[48:49], v[40:41]
	v_pk_mul_f32 v[10:11], v[52:53], v[42:43]
	global_store_dwordx4 v[44:45], v[4:7], off nt
	global_store_dwordx4 v[44:45], v[8:11], off offset:16 nt
	global_load_dwordx4 v[4:7], v[24:25], off
	s_nop 0
	global_load_dwordx4 v[8:11], v[24:25], off offset:16
	v_lshlrev_b32_e32 v40, 16, v0
	v_and_b32_e32 v41, 0xffff0000, v0
	v_lshlrev_b32_e32 v0, 16, v1
	v_and_b32_e32 v1, 0xffff0000, v1
	v_lshlrev_b32_e32 v42, 16, v2
	v_and_b32_e32 v43, 0xffff0000, v2
	v_lshlrev_b32_e32 v2, 16, v3
	v_and_b32_e32 v3, 0xffff0000, v3
	v_pk_mul_f32 v[40:41], v[32:33], v[40:41] op_sel_hi:[0,1]
	v_pk_mul_f32 v[46:47], v[32:33], v[0:1] op_sel_hi:[0,1]
	v_pk_mul_f32 v[42:43], v[32:33], v[42:43] op_sel_hi:[0,1]
	v_pk_mul_f32 v[48:49], v[32:33], v[2:3] op_sel_hi:[0,1]
	s_waitcnt vmcnt(1)
	v_pk_mul_f32 v[0:1], v[40:41], v[4:5]
	v_pk_mul_f32 v[2:3], v[46:47], v[6:7]
	s_waitcnt vmcnt(0)
	v_pk_mul_f32 v[4:5], v[42:43], v[8:9]
	v_pk_mul_f32 v[6:7], v[48:49], v[10:11]
	global_store_dwordx4 v[44:45], v[0:3], off offset:2048 nt
	global_store_dwordx4 v[44:45], v[4:7], off offset:2064 nt
	s_cbranch_scc1 .LBB0_617
